# v4
# speedup vs baseline: 1.0098x; 1.0014x over previous
; __device__ __forceinline__ void phase_attn(const Params& p, char* shm) {
;   const u16* Q = (const u16*)(p.ws + OFF_Q); const u16* KV = (const u16*)p.out; const u16* KR = (const u16*)(p.ws + OFF_KR);
;   const u16* GA = (const u16*)(p.ws + OFF_GA); u16* MG = (u16*)(p.ws + OFF_GB);
;   for (int it = blockIdx.x; it < 2560; it += gridDim.x) {
;     int head, qblk, start, len;
;     if (it < 512) { const int r = it >> 8, b = it & 255; head = b & 7; qblk = r * 32 + (b >> 3); start = 0; len = TP; }
;     else { const int j = it - 512, r = j >> 8, b = j & 255; head = b & 7; const int sl = (b >> 3) >> 4; qblk = (b >> 3) & 15;
;            start = TP + (r * 2 + sl) * 4096; len = 4096; }
;     const long row0 = start + qblk * 256;
;     attn_item(Q + row0 * LDQ + head * 192, KV + (long)start * LDK + head * 256, KV + (long)start * LDK + head * 256 + 128,
;               KR + (long)start * LDKR, GA + row0 * DM + head * 128, MG + row0 * DM + head * 128, len, shm);
;   }
.LBB0_345:
	s_or_b64 exec, exec, s[6:7]
	s_cmpk_gt_i32 s2, 0x9ff
	s_barrier
	s_cbranch_scc1 .LBB0_369
	v_readfirstlane_b32 s99, v200
	s_nop 3
	s_cmp_ge_u32 s99, 0x100
	s_cbranch_scc0 .Lnoprio4
	s_setprio 1
.Lnoprio4:
	v_readlane_b32 s8, v255, 0
	v_readlane_b32 s10, v255, 2
	v_readlane_b32 s11, v255, 3
	s_add_u32 s3, s10, 0x3ac00000
	s_addc_u32 s29, s11, 0
	s_add_u32 s53, s10, 0x16800000
	s_addc_u32 s64, s11, 0
	s_add_u32 s26, s10, 0x3ac04000
	s_addc_u32 s27, s11, 0
	v_readlane_b32 s9, v255, 1
	s_add_u32 s42, s8, 0x80000
	s_mov_b64 s[40:41], 0x80000
	s_addc_u32 s43, s9, 0
	s_movk_i32 s65, 0xc00
	s_mov_b32 s45, 0
	v_mov_b32_e32 v129, 0
	s_movk_i32 s68, 0x70
	s_mov_b32 s69, 0x42ddb3d8
	s_mov_b64 s[46:47], 0x40000
	s_mov_b64 s[48:49], 0x60000
	s_mov_b32 s70, 0x40000
	s_mov_b32 s71, 0x60000
	s_movk_i32 s72, 0x2000
	s_mov_b32 s52, 0x3dd53b94
	v_mov_b32_e32 v152, 0xf149f2ca
	s_mov_b32 s73, 0x20000
	s_mov_b64 s[56:57], 0x4000
	s_mov_b32 s74, s2
	s_mov_b32 s75, s33
	v_readlane_b32 s12, v255, 4
	v_readlane_b32 s13, v255, 5
	v_readlane_b32 s14, v255, 6
	v_readlane_b32 s15, v255, 7
	v_readlane_b32 s16, v255, 8
	v_readlane_b32 s17, v255, 9
	v_readlane_b32 s18, v255, 10
	v_readlane_b32 s19, v255, 11
	v_readlane_b32 s20, v255, 12
	v_readlane_b32 s21, v255, 13
	v_readlane_b32 s22, v255, 14
	v_readlane_b32 s23, v255, 15
	s_branch .LBB0_348

; __device__ __forceinline__ void grid_bar(unsigned* cnt, unsigned target) {
;   asm volatile("s_waitcnt vmcnt(0)" ::: "memory");
;   __syncthreads();
;   if (threadIdx.x == 0) {
;     __builtin_amdgcn_fence(__ATOMIC_RELEASE, "agent");
;     asm volatile("s_waitcnt vmcnt(0)" ::: "memory");
;     __hip_atomic_fetch_add(cnt, 1u, __ATOMIC_RELAXED, __HIP_MEMORY_SCOPE_AGENT);
;     while (__hip_atomic_load(cnt, __ATOMIC_RELAXED, __HIP_MEMORY_SCOPE_AGENT) < target) __builtin_amdgcn_s_sleep(4);
;     __builtin_amdgcn_fence(__ATOMIC_ACQUIRE, "agent");
;   }
;   __syncthreads();
; }
.LBB0_369:
	s_setprio 0
	s_waitcnt vmcnt(0)
	v_readlane_b32 s0, v255, 50
	v_readlane_b32 s1, v255, 51
	s_barrier
	s_and_saveexec_b64 s[6:7], s[0:1]
	s_cbranch_execz .LBB0_375
	s_mov_b64 s[8:9], exec
	buffer_wbl2 sc1
	s_waitcnt vmcnt(0)
	s_waitcnt vmcnt(0)
	v_mbcnt_lo_u32_b32 v0, s8, 0
	v_mbcnt_hi_u32_b32 v0, s9, v0
	v_cmp_eq_u32_e32 vcc, 0, v0
	s_and_saveexec_b64 s[10:11], vcc
	s_cbranch_execz .LBB0_372
	s_bcnt1_i32_b64 s3, s[8:9]
	v_mov_b32_e32 v0, 0
	v_mov_b32_e32 v1, s3
	global_atomic_add v0, v1, s[30:31]
